# rows phases 0/6/9: wave_sum xor-butterfly done with v_permlane32/16_swap + DPP row_ror/quad_perm moves instead of six ds_bpermute LDS round trips per sum (same pairs and order)
# speedup vs baseline: 1.0084x; 1.0018x over previous
.LBB0_45:
	s_or_b64 exec, exec, s[10:11]
	s_waitcnt vmcnt(0)
	v_mov_b32_e32 v5, v4
	v_mov_b32_e32 v184, v4
	s_nop 1
	v_permlane32_swap_b32_e32 v5, v184
	v_lshlrev_b32_e32 v132, 16, v0
	v_and_b32_e32 v133, 0xffff0000, v0
	v_lshlrev_b32_e32 v134, 16, v1
	v_and_b32_e32 v135, 0xffff0000, v1
	s_waitcnt lgkmcnt(0)
	v_add_f32_e32 v4, v5, v184
	v_mov_b32_e32 v5, v4
	v_mov_b32_e32 v185, v4
	s_nop 1
	v_permlane16_swap_b32_e32 v5, v185
	s_waitcnt lgkmcnt(0)
	v_add_f32_e32 v4, v5, v185
	s_nop 1
	v_mov_b32_dpp v5, v4 row_ror:8 row_mask:0xf bank_mask:0xf
	s_waitcnt lgkmcnt(0)
	v_add_f32_e32 v6, v4, v5
	s_nop 1
	v_mov_b32_dpp v7, v6 row_ror:4 row_mask:0xf bank_mask:0xa
	v_mov_b32_dpp v7, v6 row_ror:12 row_mask:0xf bank_mask:0x5
	v_lshlrev_b64 v[4:5], 12, v[2:3]
	v_lshlrev_b64 v[2:3], 11, v[2:3]
	v_lshl_add_u64 v[0:1], v[70:71], 0, v[4:5]
	v_lshl_add_u64 v[86:87], v[78:79], 0, v[2:3]
	s_waitcnt lgkmcnt(0)
	v_add_f32_e32 v6, v6, v7
	s_nop 1
	v_mov_b32_dpp v7, v6 quad_perm:[2,3,0,1] row_mask:0xf bank_mask:0xf
	s_waitcnt lgkmcnt(0)
	v_add_f32_e32 v88, v6, v7
	s_nop 1
	v_mov_b32_dpp v89, v88 quad_perm:[1,0,3,2] row_mask:0xf bank_mask:0xf
	global_load_dwordx4 v[12:15], v[0:1], off nt
	global_load_dwordx4 v[8:11], v[0:1], off offset:1024 nt
	global_load_dwordx4 v[4:7], v[0:1], off offset:2048 nt
	s_nop 0
	global_load_dwordx4 v[0:3], v[0:1], off offset:3072 nt
	s_waitcnt lgkmcnt(0)
	v_add_f32_e32 v88, v88, v89
	v_fmamk_f32 v88, v88, 0x3a800000, v198
	v_mul_f32_e32 v89, 0x4b800000, v88
	v_cmp_gt_f32_e64 s[10:11], s51, v88
	s_nop 1
	v_cndmask_b32_e64 v88, v88, v89, s[10:11]
	v_rsq_f32_e32 v113, v88
	global_load_dwordx2 v[96:97], v[86:87], off nt
	global_load_dwordx2 v[90:91], v[86:87], off offset:512 nt
	global_load_dwordx2 v[88:89], v[86:87], off offset:1024 nt
	s_nop 0
	global_load_dwordx2 v[86:87], v[86:87], off offset:1536 nt
	v_mul_f32_e32 v136, 0x45800000, v113
	v_cndmask_b32_e64 v136, v113, v136, s[10:11]
	v_pk_mul_f32 v[132:133], v[136:137], v[132:133] op_sel_hi:[0,1]
	v_pk_mul_f32 v[134:135], v[136:137], v[134:135] op_sel_hi:[0,1]
	v_pk_fma_f32 v[60:61], v[152:153], v[132:133], v[60:61]
	v_pk_fma_f32 v[62:63], v[154:155], v[134:135], v[62:63]
	global_store_dwordx4 v[84:85], v[60:63], off offset:-3072 nt
	v_lshlrev_b32_e32 v128, 16, v120
	v_and_b32_e32 v129, 0xffff0000, v120
	v_lshlrev_b32_e32 v120, 16, v121
	v_and_b32_e32 v121, 0xffff0000, v121
	v_pk_mul_f32 v[128:129], v[136:137], v[128:129] op_sel_hi:[0,1]
	v_pk_mul_f32 v[120:121], v[136:137], v[120:121] op_sel_hi:[0,1]
	v_pk_fma_f32 v[56:57], v[156:157], v[128:129], v[56:57]
	v_pk_fma_f32 v[58:59], v[120:121], v[158:159], v[58:59]
	global_store_dwordx4 v[84:85], v[56:59], off offset:-2048 nt
	v_lshlrev_b32_e32 v60, 16, v118
	v_and_b32_e32 v61, 0xffff0000, v118
	v_lshlrev_b32_e32 v62, 16, v119
	v_and_b32_e32 v63, 0xffff0000, v119
	v_pk_mul_f32 v[60:61], v[136:137], v[60:61] op_sel_hi:[0,1]
	v_pk_mul_f32 v[62:63], v[136:137], v[62:63] op_sel_hi:[0,1]
	v_pk_fma_f32 v[52:53], v[60:61], v[160:161], v[52:53]
	v_pk_fma_f32 v[54:55], v[62:63], v[162:163], v[54:55]
	global_store_dwordx4 v[84:85], v[52:55], off offset:-1024 nt
	v_lshlrev_b32_e32 v56, 16, v116
	v_and_b32_e32 v57, 0xffff0000, v116
	v_lshlrev_b32_e32 v58, 16, v117
	v_and_b32_e32 v59, 0xffff0000, v117
	v_pk_mul_f32 v[56:57], v[136:137], v[56:57] op_sel_hi:[0,1]
	v_pk_mul_f32 v[58:59], v[136:137], v[58:59] op_sel_hi:[0,1]
	v_pk_fma_f32 v[48:49], v[56:57], v[166:167], v[48:49]
	v_pk_fma_f32 v[50:51], v[58:59], v[168:169], v[50:51]
	global_store_dwordx4 v[84:85], v[48:51], off nt
	s_and_saveexec_b64 s[10:11], s[8:9]
	s_cbranch_execnz .LBB0_48
	s_or_b64 exec, exec, s[10:11]
	s_and_saveexec_b64 s[8:9], s[6:7]
	s_cbranch_execnz .LBB0_49

.LBB0_48:
	v_mov_b32_e32 v48, v103
	v_mov_b32_e32 v186, v103
	s_nop 1
	v_permlane32_swap_b32_e32 v48, v186
	v_lshlrev_b32_e32 v56, 16, v114
	v_and_b32_e32 v57, 0xffff0000, v114
	v_ashrrev_i32_e32 v113, 31, v112
	v_lshlrev_b32_e32 v58, 16, v115
	s_waitcnt lgkmcnt(0)
	v_add_f32_e32 v48, v48, v186
	v_mov_b32_e32 v49, v48
	v_mov_b32_e32 v187, v48
	s_nop 1
	v_permlane16_swap_b32_e32 v49, v187
	v_and_b32_e32 v59, 0xffff0000, v115
	s_waitcnt lgkmcnt(0)
	v_add_f32_e32 v48, v49, v187
	s_nop 1
	v_mov_b32_dpp v49, v48 row_ror:8 row_mask:0xf bank_mask:0xf
	s_waitcnt lgkmcnt(0)
	v_add_f32_e32 v48, v48, v49
	s_nop 1
	v_mov_b32_dpp v49, v48 row_ror:4 row_mask:0xf bank_mask:0xa
	v_mov_b32_dpp v49, v48 row_ror:12 row_mask:0xf bank_mask:0x5
	s_waitcnt lgkmcnt(0)
	v_add_f32_e32 v48, v48, v49
	s_nop 1
	v_mov_b32_dpp v49, v48 quad_perm:[2,3,0,1] row_mask:0xf bank_mask:0xf
	s_waitcnt lgkmcnt(0)
	v_add_f32_e32 v48, v48, v49
	s_nop 1
	v_mov_b32_dpp v49, v48 quad_perm:[1,0,3,2] row_mask:0xf bank_mask:0xf
	s_waitcnt lgkmcnt(0)
	v_add_f32_e32 v48, v48, v49
	v_fmamk_f32 v48, v48, 0x3a800000, v198
	v_cmp_gt_f32_e64 s[8:9], s51, v48
	v_mul_f32_e32 v49, 0x4b800000, v48
	s_nop 0
	v_cndmask_b32_e64 v48, v48, v49, s[8:9]
	v_rsq_f32_e32 v48, v48
	s_nop 0
	v_mul_f32_e32 v49, 0x45800000, v48
	v_cndmask_b32_e64 v50, v48, v49, s[8:9]
	v_pk_mul_f32 v[56:57], v[50:51], v[56:57] op_sel_hi:[0,1]
	v_lshlrev_b64 v[48:49], 12, v[112:113]
	v_pk_fma_f32 v[44:45], v[152:153], v[56:57], v[44:45]
	v_pk_mul_f32 v[52:53], v[50:51], v[58:59] op_sel_hi:[0,1]
	v_pk_fma_f32 v[46:47], v[154:155], v[52:53], v[46:47]
	v_lshl_add_u64 v[52:53], v[70:71], 0, v[48:49]
	global_store_dwordx4 v[52:53], v[44:47], off nt
	v_lshlrev_b32_e32 v52, 16, v110
	v_and_b32_e32 v53, 0xffff0000, v110
	v_lshlrev_b32_e32 v54, 16, v111
	v_and_b32_e32 v55, 0xffff0000, v111
	v_pk_mul_f32 v[52:53], v[50:51], v[52:53] op_sel_hi:[0,1]
	v_pk_mul_f32 v[54:55], v[50:51], v[54:55] op_sel_hi:[0,1]
	v_lshl_add_u64 v[56:57], v[72:73], 0, v[48:49]
	v_pk_fma_f32 v[40:41], v[156:157], v[52:53], v[40:41]
	v_pk_fma_f32 v[42:43], v[54:55], v[158:159], v[42:43]
	global_store_dwordx4 v[56:57], v[40:43], off nt
	v_lshlrev_b32_e32 v44, 16, v108
	v_and_b32_e32 v45, 0xffff0000, v108
	v_lshlrev_b32_e32 v46, 16, v109
	v_and_b32_e32 v47, 0xffff0000, v109
	v_pk_mul_f32 v[44:45], v[50:51], v[44:45] op_sel_hi:[0,1]
	v_pk_fma_f32 v[36:37], v[44:45], v[160:161], v[36:37]
	v_pk_mul_f32 v[40:41], v[50:51], v[46:47] op_sel_hi:[0,1]
	v_pk_fma_f32 v[38:39], v[40:41], v[162:163], v[38:39]
	v_lshl_add_u64 v[40:41], v[74:75], 0, v[48:49]
	global_store_dwordx4 v[40:41], v[36:39], off nt
	v_lshlrev_b32_e32 v40, 16, v106
	v_and_b32_e32 v41, 0xffff0000, v106
	v_lshlrev_b32_e32 v42, 16, v107
	v_and_b32_e32 v43, 0xffff0000, v107
	v_pk_mul_f32 v[40:41], v[50:51], v[40:41] op_sel_hi:[0,1]
	v_pk_fma_f32 v[32:33], v[40:41], v[166:167], v[32:33]
	v_pk_mul_f32 v[36:37], v[50:51], v[42:43] op_sel_hi:[0,1]
	v_pk_fma_f32 v[34:35], v[36:37], v[168:169], v[34:35]
	v_lshl_add_u64 v[36:37], v[76:77], 0, v[48:49]
	global_store_dwordx4 v[36:37], v[32:35], off nt
	s_or_b64 exec, exec, s[10:11]
	s_and_saveexec_b64 s[8:9], s[6:7]
	s_cbranch_execz .LBB0_47
.LBB0_49:
	v_mov_b32_e32 v32, v93
	v_mov_b32_e32 v188, v93
	s_nop 1
	v_permlane32_swap_b32_e32 v32, v188
	v_lshlrev_b32_e32 v40, 16, v104
	v_and_b32_e32 v41, 0xffff0000, v104
	v_ashrrev_i32_e32 v103, 31, v102
	v_lshlrev_b32_e32 v42, 16, v105
	s_waitcnt lgkmcnt(0)
	v_add_f32_e32 v32, v32, v188
	v_mov_b32_e32 v33, v32
	v_mov_b32_e32 v189, v32
	s_nop 1
	v_permlane16_swap_b32_e32 v33, v189
	v_and_b32_e32 v43, 0xffff0000, v105
	s_waitcnt lgkmcnt(0)
	v_add_f32_e32 v32, v33, v189
	s_nop 1
	v_mov_b32_dpp v33, v32 row_ror:8 row_mask:0xf bank_mask:0xf
	s_waitcnt lgkmcnt(0)
	v_add_f32_e32 v32, v32, v33
	s_nop 1
	v_mov_b32_dpp v33, v32 row_ror:4 row_mask:0xf bank_mask:0xa
	v_mov_b32_dpp v33, v32 row_ror:12 row_mask:0xf bank_mask:0x5
	s_waitcnt lgkmcnt(0)
	v_add_f32_e32 v32, v32, v33
	s_nop 1
	v_mov_b32_dpp v33, v32 quad_perm:[2,3,0,1] row_mask:0xf bank_mask:0xf
	s_waitcnt lgkmcnt(0)
	v_add_f32_e32 v32, v32, v33
	s_nop 1
	v_mov_b32_dpp v33, v32 quad_perm:[1,0,3,2] row_mask:0xf bank_mask:0xf
	s_waitcnt lgkmcnt(0)
	v_add_f32_e32 v32, v32, v33
	v_fmamk_f32 v32, v32, 0x3a800000, v198
	v_cmp_gt_f32_e64 s[6:7], s51, v32
	v_mul_f32_e32 v33, 0x4b800000, v32
	s_nop 0
	v_cndmask_b32_e64 v32, v32, v33, s[6:7]
	v_rsq_f32_e32 v32, v32
	s_nop 0
	v_mul_f32_e32 v33, 0x45800000, v32
	v_cndmask_b32_e64 v34, v32, v33, s[6:7]
	v_pk_mul_f32 v[40:41], v[34:35], v[40:41] op_sel_hi:[0,1]
	v_lshlrev_b64 v[32:33], 12, v[102:103]
	v_pk_fma_f32 v[28:29], v[152:153], v[40:41], v[28:29]
	v_pk_mul_f32 v[36:37], v[34:35], v[42:43] op_sel_hi:[0,1]
	v_pk_fma_f32 v[30:31], v[154:155], v[36:37], v[30:31]
	v_lshl_add_u64 v[36:37], v[70:71], 0, v[32:33]
	global_store_dwordx4 v[36:37], v[28:31], off nt
	v_lshlrev_b32_e32 v36, 16, v100
	v_and_b32_e32 v37, 0xffff0000, v100
	v_lshlrev_b32_e32 v38, 16, v101
	v_and_b32_e32 v39, 0xffff0000, v101
	v_pk_mul_f32 v[36:37], v[34:35], v[36:37] op_sel_hi:[0,1]
	v_pk_mul_f32 v[38:39], v[34:35], v[38:39] op_sel_hi:[0,1]
	v_lshl_add_u64 v[40:41], v[72:73], 0, v[32:33]
	v_pk_fma_f32 v[24:25], v[156:157], v[36:37], v[24:25]
	v_pk_fma_f32 v[26:27], v[38:39], v[158:159], v[26:27]
	global_store_dwordx4 v[40:41], v[24:27], off nt
	v_lshlrev_b32_e32 v28, 16, v98
	v_and_b32_e32 v29, 0xffff0000, v98
	v_lshlrev_b32_e32 v30, 16, v99
	v_and_b32_e32 v31, 0xffff0000, v99
	v_pk_mul_f32 v[28:29], v[34:35], v[28:29] op_sel_hi:[0,1]
	v_pk_fma_f32 v[20:21], v[28:29], v[160:161], v[20:21]
	v_pk_mul_f32 v[24:25], v[34:35], v[30:31] op_sel_hi:[0,1]
	v_pk_fma_f32 v[22:23], v[24:25], v[162:163], v[22:23]
	v_lshl_add_u64 v[24:25], v[74:75], 0, v[32:33]
	global_store_dwordx4 v[24:25], v[20:23], off nt
	v_lshlrev_b32_e32 v24, 16, v94
	v_and_b32_e32 v25, 0xffff0000, v94
	v_lshlrev_b32_e32 v26, 16, v95
	v_and_b32_e32 v27, 0xffff0000, v95
	v_pk_mul_f32 v[24:25], v[34:35], v[24:25] op_sel_hi:[0,1]
	v_pk_fma_f32 v[16:17], v[24:25], v[166:167], v[16:17]
	v_pk_mul_f32 v[20:21], v[34:35], v[26:27] op_sel_hi:[0,1]
	v_pk_fma_f32 v[18:19], v[20:21], v[168:169], v[18:19]
	v_lshl_add_u64 v[20:21], v[76:77], 0, v[32:33]
	global_store_dwordx4 v[20:21], v[16:19], off nt
	s_or_b64 exec, exec, s[8:9]
	s_and_saveexec_b64 s[6:7], s[4:5]
	s_cbranch_execz .LBB0_36
.LBB0_50:
	s_waitcnt vmcnt(0)
	v_mov_b32_e32 v16, v65
	v_mov_b32_e32 v184, v65
	s_nop 1
	v_permlane32_swap_b32_e32 v16, v184
	v_lshlrev_b32_e32 v24, 16, v96
	v_and_b32_e32 v25, 0xffff0000, v96
	v_ashrrev_i32_e32 v93, 31, v92
	v_lshlrev_b32_e32 v26, 16, v97
	s_waitcnt lgkmcnt(0)
	v_add_f32_e32 v16, v16, v184
	v_mov_b32_e32 v17, v16
	v_mov_b32_e32 v185, v16
	s_nop 1
	v_permlane16_swap_b32_e32 v17, v185
	v_and_b32_e32 v27, 0xffff0000, v97
	s_waitcnt lgkmcnt(0)
	v_add_f32_e32 v16, v17, v185
	s_nop 1
	v_mov_b32_dpp v17, v16 row_ror:8 row_mask:0xf bank_mask:0xf
	s_waitcnt lgkmcnt(0)
	v_add_f32_e32 v16, v16, v17
	s_nop 1
	v_mov_b32_dpp v17, v16 row_ror:4 row_mask:0xf bank_mask:0xa
	v_mov_b32_dpp v17, v16 row_ror:12 row_mask:0xf bank_mask:0x5
	s_waitcnt lgkmcnt(0)
	v_add_f32_e32 v16, v16, v17
	s_nop 1
	v_mov_b32_dpp v17, v16 quad_perm:[2,3,0,1] row_mask:0xf bank_mask:0xf
	s_waitcnt lgkmcnt(0)
	v_add_f32_e32 v16, v16, v17
	s_nop 1
	v_mov_b32_dpp v17, v16 quad_perm:[1,0,3,2] row_mask:0xf bank_mask:0xf
	s_waitcnt lgkmcnt(0)
	v_add_f32_e32 v16, v16, v17
	v_fmamk_f32 v16, v16, 0x3a800000, v198
	v_cmp_gt_f32_e64 s[4:5], s51, v16
	v_mul_f32_e32 v17, 0x4b800000, v16
	s_nop 0
	v_cndmask_b32_e64 v16, v16, v17, s[4:5]
	v_rsq_f32_e32 v16, v16
	s_nop 0
	v_mul_f32_e32 v17, 0x45800000, v16
	v_cndmask_b32_e64 v18, v16, v17, s[4:5]
	v_pk_mul_f32 v[24:25], v[18:19], v[24:25] op_sel_hi:[0,1]
	v_lshlrev_b64 v[16:17], 12, v[92:93]
	v_pk_fma_f32 v[12:13], v[152:153], v[24:25], v[12:13]
	v_pk_mul_f32 v[20:21], v[18:19], v[26:27] op_sel_hi:[0,1]
	v_pk_fma_f32 v[14:15], v[154:155], v[20:21], v[14:15]
	v_lshl_add_u64 v[20:21], v[70:71], 0, v[16:17]
	global_store_dwordx4 v[20:21], v[12:15], off nt
	v_lshlrev_b32_e32 v20, 16, v90
	v_and_b32_e32 v21, 0xffff0000, v90
	v_lshlrev_b32_e32 v22, 16, v91
	v_and_b32_e32 v23, 0xffff0000, v91
	v_pk_mul_f32 v[20:21], v[18:19], v[20:21] op_sel_hi:[0,1]
	v_pk_mul_f32 v[22:23], v[18:19], v[22:23] op_sel_hi:[0,1]
	v_lshl_add_u64 v[24:25], v[72:73], 0, v[16:17]
	v_pk_fma_f32 v[8:9], v[156:157], v[20:21], v[8:9]
	v_pk_fma_f32 v[10:11], v[22:23], v[158:159], v[10:11]
	global_store_dwordx4 v[24:25], v[8:11], off nt
	v_lshlrev_b32_e32 v12, 16, v88
	v_and_b32_e32 v13, 0xffff0000, v88
	v_lshlrev_b32_e32 v14, 16, v89
	v_and_b32_e32 v15, 0xffff0000, v89
	v_pk_mul_f32 v[12:13], v[18:19], v[12:13] op_sel_hi:[0,1]
	v_pk_fma_f32 v[4:5], v[12:13], v[160:161], v[4:5]
	v_pk_mul_f32 v[8:9], v[18:19], v[14:15] op_sel_hi:[0,1]
	v_pk_fma_f32 v[6:7], v[8:9], v[162:163], v[6:7]
	v_lshl_add_u64 v[8:9], v[74:75], 0, v[16:17]
	global_store_dwordx4 v[8:9], v[4:7], off nt
	v_lshlrev_b32_e32 v8, 16, v86
	v_and_b32_e32 v9, 0xffff0000, v86
	v_lshlrev_b32_e32 v10, 16, v87
	v_and_b32_e32 v11, 0xffff0000, v87
	v_pk_mul_f32 v[8:9], v[18:19], v[8:9] op_sel_hi:[0,1]
	v_pk_fma_f32 v[0:1], v[8:9], v[166:167], v[0:1]
	v_pk_mul_f32 v[4:5], v[18:19], v[10:11] op_sel_hi:[0,1]
	v_pk_fma_f32 v[2:3], v[4:5], v[168:169], v[2:3]
	v_lshl_add_u64 v[4:5], v[76:77], 0, v[16:17]
	global_store_dwordx4 v[4:5], v[0:3], off nt
	s_branch .LBB0_36

.LBB0_94:
	s_or_b64 exec, exec, s[10:11]
	s_waitcnt vmcnt(0)
	v_mov_b32_e32 v5, v4
	v_mov_b32_e32 v184, v4
	s_nop 1
	v_permlane32_swap_b32_e32 v5, v184
	v_lshlrev_b32_e32 v134, 16, v0
	v_and_b32_e32 v135, 0xffff0000, v0
	v_lshlrev_b32_e32 v136, 16, v1
	v_and_b32_e32 v137, 0xffff0000, v1
	s_waitcnt lgkmcnt(0)
	v_add_f32_e32 v4, v5, v184
	v_mov_b32_e32 v5, v4
	v_mov_b32_e32 v185, v4
	s_nop 1
	v_permlane16_swap_b32_e32 v5, v185
	v_lshl_add_u64 v[138:139], v[86:87], 0, v[196:197]
	v_readlane_b32 s72, v250, 53
	v_readlane_b32 s78, v250, 59
	v_readlane_b32 s79, v250, 60
	s_waitcnt lgkmcnt(0)
	v_add_f32_e32 v6, v5, v185
	s_nop 1
	v_mov_b32_dpp v7, v6 row_ror:8 row_mask:0xf bank_mask:0xf
	v_lshlrev_b64 v[4:5], 12, v[2:3]
	v_lshlrev_b64 v[2:3], 11, v[2:3]
	v_lshl_add_u64 v[0:1], v[76:77], 0, v[4:5]
	v_lshl_add_u64 v[90:91], v[78:79], 0, v[2:3]
	s_waitcnt lgkmcnt(0)
	v_add_f32_e32 v6, v6, v7
	s_nop 1
	v_mov_b32_dpp v7, v6 row_ror:4 row_mask:0xf bank_mask:0xa
	v_mov_b32_dpp v7, v6 row_ror:12 row_mask:0xf bank_mask:0x5
	v_readlane_b32 s73, v250, 54
	v_readlane_b32 s74, v250, 55
	v_readlane_b32 s75, v250, 56
	v_readlane_b32 s76, v250, 57
	s_waitcnt lgkmcnt(0)
	v_add_f32_e32 v6, v6, v7
	s_nop 1
	v_mov_b32_dpp v7, v6 quad_perm:[2,3,0,1] row_mask:0xf bank_mask:0xf
	v_readlane_b32 s77, v250, 58
	v_readlane_b32 s80, v250, 61
	v_readlane_b32 s81, v250, 62
	v_readlane_b32 s82, v250, 63
	s_waitcnt lgkmcnt(0)
	v_add_f32_e32 v92, v6, v7
	s_nop 1
	v_mov_b32_dpp v93, v92 quad_perm:[1,0,3,2] row_mask:0xf bank_mask:0xf
	global_load_dwordx4 v[12:15], v[0:1], off nt
	global_load_dwordx4 v[8:11], v[0:1], off offset:1024 nt
	global_load_dwordx4 v[4:7], v[0:1], off offset:2048 nt
	s_nop 0
	global_load_dwordx4 v[0:3], v[0:1], off offset:3072 nt
	v_readlane_b32 s83, v249, 0
	v_readlane_b32 s84, v249, 1
	v_readlane_b32 s85, v249, 2
	s_waitcnt lgkmcnt(0)
	v_add_f32_e32 v92, v92, v93
	v_fmamk_f32 v92, v92, 0x3a800000, v198
	v_mul_f32_e32 v93, 0x4b800000, v92
	v_cmp_gt_f32_e64 s[10:11], s51, v92
	v_readlane_b32 s86, v249, 3
	v_readlane_b32 s87, v249, 4
	v_cndmask_b32_e64 v92, v92, v93, s[10:11]
	v_rsq_f32_e32 v109, v92
	global_load_dwordx2 v[98:99], v[90:91], off nt
	global_load_dwordx2 v[94:95], v[90:91], off offset:512 nt
	global_load_dwordx2 v[92:93], v[90:91], off offset:1024 nt
	s_nop 0
	global_load_dwordx2 v[90:91], v[90:91], off offset:1536 nt
	v_mul_f32_e32 v140, 0x45800000, v109
	v_cndmask_b32_e64 v140, v109, v140, s[10:11]
	v_pk_mul_f32 v[134:135], v[140:141], v[134:135] op_sel_hi:[0,1]
	v_pk_mul_f32 v[136:137], v[140:141], v[136:137] op_sel_hi:[0,1]
	v_pk_fma_f32 v[60:61], v[142:143], v[134:135], v[60:61]
	v_pk_fma_f32 v[62:63], v[144:145], v[136:137], v[62:63]
	global_store_dwordx4 v[138:139], v[60:63], off
	v_lshlrev_b32_e32 v134, 16, v122
	v_and_b32_e32 v135, 0xffff0000, v122
	v_lshlrev_b32_e32 v122, 16, v123
	v_and_b32_e32 v123, 0xffff0000, v123
	v_pk_mul_f32 v[134:135], v[140:141], v[134:135] op_sel_hi:[0,1]
	v_pk_mul_f32 v[122:123], v[140:141], v[122:123] op_sel_hi:[0,1]
	v_pk_fma_f32 v[56:57], v[134:135], v[146:147], v[56:57]
	v_pk_fma_f32 v[58:59], v[122:123], v[148:149], v[58:59]
	global_store_dwordx4 v[138:139], v[56:59], off offset:1024
	v_lshlrev_b32_e32 v122, 16, v120
	v_and_b32_e32 v123, 0xffff0000, v120
	v_lshlrev_b32_e32 v120, 16, v121
	v_and_b32_e32 v121, 0xffff0000, v121
	v_pk_mul_f32 v[122:123], v[140:141], v[122:123] op_sel_hi:[0,1]
	v_pk_mul_f32 v[120:121], v[140:141], v[120:121] op_sel_hi:[0,1]
	v_mov_b32_e32 v134, v63
	v_mov_b32_e32 v135, v59
	v_pk_fma_f32 v[52:53], v[122:123], v[152:153], v[52:53]
	v_pk_fma_f32 v[54:55], v[120:121], v[154:155], v[54:55]
	global_store_dwordx4 v[138:139], v[52:55], off offset:2048
	v_lshlrev_b32_e32 v130, 16, v118
	v_and_b32_e32 v131, 0xffff0000, v118
	v_lshlrev_b32_e32 v118, 16, v119
	v_and_b32_e32 v119, 0xffff0000, v119
	v_pk_mul_f32 v[130:131], v[140:141], v[130:131] op_sel_hi:[0,1]
	v_pk_mul_f32 v[118:119], v[140:141], v[118:119] op_sel_hi:[0,1]
	v_mov_b32_e32 v132, v62
	v_mov_b32_e32 v133, v58
	v_pk_fma_f32 v[48:49], v[130:131], v[156:157], v[48:49]
	v_pk_fma_f32 v[50:51], v[118:119], v[158:159], v[50:51]
	global_store_dwordx4 v[138:139], v[48:51], off offset:3072
	v_mov_b32_e32 v130, v61
	v_mov_b32_e32 v131, v57
	v_mov_b32_e32 v122, v60
	v_mov_b32_e32 v123, v56
	v_pk_mul_f32 v[130:131], v[130:131], v[130:131]
	s_nop 0
	v_pk_fma_f32 v[122:123], v[122:123], v[122:123], v[130:131]
	v_mov_b32_e32 v130, v53
	v_pk_fma_f32 v[122:123], v[132:133], v[132:133], v[122:123]
	v_mov_b32_e32 v131, v49
	v_pk_fma_f32 v[122:123], v[134:135], v[134:135], v[122:123]
	v_pk_mul_f32 v[130:131], v[130:131], v[130:131]
	v_add_f32_e32 v109, v122, v123
	v_mov_b32_e32 v122, v52
	v_mov_b32_e32 v123, v48
	v_mov_b32_e32 v132, v54
	v_mov_b32_e32 v133, v50
	v_pk_fma_f32 v[122:123], v[122:123], v[122:123], v[130:131]
	v_mov_b32_e32 v134, v55
	v_mov_b32_e32 v135, v51
	v_pk_fma_f32 v[122:123], v[132:133], v[132:133], v[122:123]
	s_nop 0
	v_pk_fma_f32 v[122:123], v[134:135], v[134:135], v[122:123]
	s_nop 0
	v_add_f32_e32 v109, v109, v122
	v_add_f32_e32 v109, v109, v123
	v_mov_b32_e32 v122, v109
	v_mov_b32_e32 v186, v109
	s_nop 1
	v_permlane32_swap_b32_e32 v122, v186
	s_waitcnt lgkmcnt(0)
	v_add_f32_e32 v109, v122, v186
	v_mov_b32_e32 v122, v109
	v_mov_b32_e32 v187, v109
	s_nop 1
	v_permlane16_swap_b32_e32 v122, v187
	s_waitcnt lgkmcnt(0)
	v_add_f32_e32 v109, v122, v187
	s_nop 1
	v_mov_b32_dpp v122, v109 row_ror:8 row_mask:0xf bank_mask:0xf
	s_waitcnt lgkmcnt(0)
	v_add_f32_e32 v109, v109, v122
	s_nop 1
	v_mov_b32_dpp v122, v109 row_ror:4 row_mask:0xf bank_mask:0xa
	v_mov_b32_dpp v122, v109 row_ror:12 row_mask:0xf bank_mask:0x5
	s_waitcnt lgkmcnt(0)
	v_add_f32_e32 v109, v109, v122
	s_nop 1
	v_mov_b32_dpp v122, v109 quad_perm:[2,3,0,1] row_mask:0xf bank_mask:0xf
	s_waitcnt lgkmcnt(0)
	v_add_f32_e32 v109, v109, v122
	s_nop 1
	v_mov_b32_dpp v122, v109 quad_perm:[1,0,3,2] row_mask:0xf bank_mask:0xf
	s_waitcnt lgkmcnt(0)
	v_add_f32_e32 v109, v109, v122
	v_fmamk_f32 v109, v109, 0x3a800000, v198
	v_mul_f32_e32 v122, 0x4b800000, v109
	v_cmp_gt_f32_e64 s[10:11], s51, v109
	s_nop 1
	v_cndmask_b32_e64 v109, v109, v122, s[10:11]
	v_rsq_f32_e32 v109, v109
	v_lshl_add_u64 v[122:123], s[78:79], 0, v[84:85]
	v_mul_f32_e32 v130, 0x45800000, v109
	v_cndmask_b32_e64 v130, v109, v130, s[10:11]
	v_pk_mul_f32 v[60:61], v[60:61], v[130:131] op_sel_hi:[1,0]
	v_pk_mul_f32 v[62:63], v[62:63], v[130:131] op_sel_hi:[1,0]
	v_pk_mul_f32 v[56:57], v[56:57], v[130:131] op_sel_hi:[1,0]
	v_pk_mul_f32 v[58:59], v[58:59], v[130:131] op_sel_hi:[1,0]
	v_pk_mul_f32 v[52:53], v[52:53], v[130:131] op_sel_hi:[1,0]
	v_pk_mul_f32 v[60:61], v[160:161], v[60:61]
	v_pk_mul_f32 v[62:63], v[162:163], v[62:63]
	v_cvt_pk_bf16_f32 v60, v60, v61
	v_cvt_pk_bf16_f32 v61, v62, v63
	global_store_dwordx2 v[122:123], v[60:61], off
	v_pk_mul_f32 v[54:55], v[54:55], v[130:131] op_sel_hi:[1,0]
	v_pk_mul_f32 v[48:49], v[48:49], v[130:131] op_sel_hi:[1,0]
	v_pk_mul_f32 v[50:51], v[50:51], v[130:131] op_sel_hi:[1,0]
	v_pk_mul_f32 v[56:57], v[166:167], v[56:57]
	v_pk_mul_f32 v[58:59], v[58:59], v[168:169]
	v_cvt_pk_bf16_f32 v56, v56, v57
	v_cvt_pk_bf16_f32 v57, v58, v59
	global_store_dwordx2 v[122:123], v[56:57], off offset:512
	v_pk_mul_f32 v[52:53], v[52:53], v[170:171]
	v_pk_mul_f32 v[54:55], v[54:55], v[172:173]
	v_cvt_pk_bf16_f32 v52, v52, v53
	v_cvt_pk_bf16_f32 v53, v54, v55
	global_store_dwordx2 v[122:123], v[52:53], off offset:1024
	v_pk_mul_f32 v[48:49], v[48:49], v[174:175]
	v_pk_mul_f32 v[50:51], v[50:51], v[176:177]
	v_cvt_pk_bf16_f32 v48, v48, v49
	v_cvt_pk_bf16_f32 v49, v50, v51
	global_store_dwordx2 v[122:123], v[48:49], off offset:1536
	s_and_saveexec_b64 s[10:11], s[8:9]
	s_cbranch_execnz .LBB0_97
	s_or_b64 exec, exec, s[10:11]
	s_and_saveexec_b64 s[8:9], s[6:7]
	s_cbranch_execnz .LBB0_98

.LBB0_97:
	v_mov_b32_e32 v52, v97
	v_mov_b32_e32 v188, v97
	s_nop 1
	v_permlane32_swap_b32_e32 v52, v188
	v_ashrrev_i32_e32 v109, 31, v108
	v_lshlrev_b32_e32 v54, 16, v117
	s_waitcnt lgkmcnt(0)
	v_add_f32_e32 v52, v52, v188
	v_mov_b32_e32 v53, v52
	v_mov_b32_e32 v189, v52
	s_nop 1
	v_permlane16_swap_b32_e32 v53, v189
	s_waitcnt lgkmcnt(0)
	v_add_f32_e32 v52, v53, v189
	s_nop 1
	v_mov_b32_dpp v53, v52 row_ror:8 row_mask:0xf bank_mask:0xf
	s_waitcnt lgkmcnt(0)
	v_add_f32_e32 v52, v52, v53
	s_nop 1
	v_mov_b32_dpp v53, v52 row_ror:4 row_mask:0xf bank_mask:0xa
	v_mov_b32_dpp v53, v52 row_ror:12 row_mask:0xf bank_mask:0x5
	s_waitcnt lgkmcnt(0)
	v_add_f32_e32 v52, v52, v53
	s_nop 1
	v_mov_b32_dpp v53, v52 quad_perm:[2,3,0,1] row_mask:0xf bank_mask:0xf
	s_waitcnt lgkmcnt(0)
	v_add_f32_e32 v55, v52, v53
	s_nop 1
	v_mov_b32_dpp v56, v55 quad_perm:[1,0,3,2] row_mask:0xf bank_mask:0xf
	v_lshlrev_b32_e32 v52, 16, v116
	v_and_b32_e32 v53, 0xffff0000, v116
	s_waitcnt lgkmcnt(0)
	v_add_f32_e32 v55, v55, v56
	v_fmamk_f32 v55, v55, 0x3a800000, v198
	v_mul_f32_e32 v56, 0x4b800000, v55
	v_cmp_gt_f32_e64 s[8:9], s51, v55
	s_nop 1
	v_cndmask_b32_e64 v55, v55, v56, s[8:9]
	v_rsq_f32_e32 v58, v55
	v_and_b32_e32 v55, 0xffff0000, v117
	v_lshlrev_b64 v[56:57], 12, v[108:109]
	v_lshl_add_u64 v[56:57], v[70:71], 0, v[56:57]
	v_mul_f32_e32 v59, 0x45800000, v58
	v_cndmask_b32_e64 v58, v58, v59, s[8:9]
	v_pk_mul_f32 v[52:53], v[58:59], v[52:53] op_sel_hi:[0,1]
	v_pk_mul_f32 v[54:55], v[58:59], v[54:55] op_sel_hi:[0,1]
	v_pk_fma_f32 v[44:45], v[142:143], v[52:53], v[44:45]
	v_pk_fma_f32 v[46:47], v[144:145], v[54:55], v[46:47]
	global_store_dwordx4 v[56:57], v[44:47], off
	v_lshlrev_b32_e32 v52, 16, v114
	v_and_b32_e32 v53, 0xffff0000, v114
	v_lshlrev_b32_e32 v54, 16, v115
	v_and_b32_e32 v55, 0xffff0000, v115
	v_pk_mul_f32 v[52:53], v[58:59], v[52:53] op_sel_hi:[0,1]
	v_pk_mul_f32 v[54:55], v[58:59], v[54:55] op_sel_hi:[0,1]
	v_pk_fma_f32 v[40:41], v[52:53], v[146:147], v[40:41]
	v_pk_fma_f32 v[42:43], v[54:55], v[148:149], v[42:43]
	global_store_dwordx4 v[56:57], v[40:43], off offset:1024
	v_lshlrev_b32_e32 v52, 16, v112
	v_and_b32_e32 v53, 0xffff0000, v112
	v_lshlrev_b32_e32 v54, 16, v113
	v_and_b32_e32 v55, 0xffff0000, v113
	v_pk_mul_f32 v[52:53], v[58:59], v[52:53] op_sel_hi:[0,1]
	v_pk_mul_f32 v[54:55], v[58:59], v[54:55] op_sel_hi:[0,1]
	v_pk_fma_f32 v[36:37], v[52:53], v[152:153], v[36:37]
	v_pk_fma_f32 v[38:39], v[54:55], v[154:155], v[38:39]
	global_store_dwordx4 v[56:57], v[36:39], off offset:2048
	v_lshlrev_b32_e32 v52, 16, v110
	v_and_b32_e32 v53, 0xffff0000, v110
	v_lshlrev_b32_e32 v54, 16, v111
	v_and_b32_e32 v55, 0xffff0000, v111
	v_pk_mul_f32 v[52:53], v[58:59], v[52:53] op_sel_hi:[0,1]
	v_pk_mul_f32 v[54:55], v[58:59], v[54:55] op_sel_hi:[0,1]
	v_mov_b32_e32 v58, v47
	v_mov_b32_e32 v59, v43
	v_pk_fma_f32 v[32:33], v[52:53], v[156:157], v[32:33]
	v_pk_fma_f32 v[34:35], v[54:55], v[158:159], v[34:35]
	global_store_dwordx4 v[56:57], v[32:35], off offset:3072
	v_mov_b32_e32 v54, v45
	v_mov_b32_e32 v55, v41
	v_mov_b32_e32 v52, v44
	v_mov_b32_e32 v53, v40
	v_pk_mul_f32 v[54:55], v[54:55], v[54:55]
	v_mov_b32_e32 v56, v46
	v_mov_b32_e32 v57, v42
	v_pk_fma_f32 v[52:53], v[52:53], v[52:53], v[54:55]
	v_mov_b32_e32 v54, v37
	v_pk_fma_f32 v[52:53], v[56:57], v[56:57], v[52:53]
	v_mov_b32_e32 v55, v33
	v_pk_fma_f32 v[52:53], v[58:59], v[58:59], v[52:53]
	v_pk_mul_f32 v[54:55], v[54:55], v[54:55]
	v_add_f32_e32 v60, v52, v53
	v_mov_b32_e32 v52, v36
	v_mov_b32_e32 v53, v32
	v_mov_b32_e32 v56, v38
	v_mov_b32_e32 v57, v34
	v_pk_fma_f32 v[52:53], v[52:53], v[52:53], v[54:55]
	v_mov_b32_e32 v58, v39
	v_mov_b32_e32 v59, v35
	v_pk_fma_f32 v[52:53], v[56:57], v[56:57], v[52:53]
	s_nop 0
	v_pk_fma_f32 v[52:53], v[58:59], v[58:59], v[52:53]
	s_nop 0
	v_add_f32_e32 v52, v60, v52
	v_add_f32_e32 v52, v52, v53
	v_mov_b32_e32 v53, v52
	v_mov_b32_e32 v184, v52
	s_nop 1
	v_permlane32_swap_b32_e32 v53, v184
	s_waitcnt lgkmcnt(0)
	v_add_f32_e32 v52, v53, v184
	v_mov_b32_e32 v53, v52
	v_mov_b32_e32 v185, v52
	s_nop 1
	v_permlane16_swap_b32_e32 v53, v185
	s_waitcnt lgkmcnt(0)
	v_add_f32_e32 v52, v53, v185
	s_nop 1
	v_mov_b32_dpp v53, v52 row_ror:8 row_mask:0xf bank_mask:0xf
	s_waitcnt lgkmcnt(0)
	v_add_f32_e32 v52, v52, v53
	s_nop 1
	v_mov_b32_dpp v53, v52 row_ror:4 row_mask:0xf bank_mask:0xa
	v_mov_b32_dpp v53, v52 row_ror:12 row_mask:0xf bank_mask:0x5
	s_waitcnt lgkmcnt(0)
	v_add_f32_e32 v52, v52, v53
	s_nop 1
	v_mov_b32_dpp v53, v52 quad_perm:[2,3,0,1] row_mask:0xf bank_mask:0xf
	s_waitcnt lgkmcnt(0)
	v_add_f32_e32 v52, v52, v53
	s_nop 1
	v_mov_b32_dpp v53, v52 quad_perm:[1,0,3,2] row_mask:0xf bank_mask:0xf
	s_waitcnt lgkmcnt(0)
	v_add_f32_e32 v52, v52, v53
	v_fmamk_f32 v52, v52, 0x3a800000, v198
	v_mul_f32_e32 v53, 0x4b800000, v52
	v_cmp_gt_f32_e64 s[8:9], s51, v52
	s_nop 1
	v_cndmask_b32_e64 v52, v52, v53, s[8:9]
	v_rsq_f32_e32 v54, v52
	v_lshlrev_b64 v[52:53], 11, v[108:109]
	v_lshl_add_u64 v[52:53], v[74:75], 0, v[52:53]
	v_mul_f32_e32 v55, 0x45800000, v54
	v_cndmask_b32_e64 v54, v54, v55, s[8:9]
	v_pk_mul_f32 v[44:45], v[44:45], v[54:55] op_sel_hi:[1,0]
	v_pk_mul_f32 v[46:47], v[46:47], v[54:55] op_sel_hi:[1,0]
	v_pk_mul_f32 v[40:41], v[40:41], v[54:55] op_sel_hi:[1,0]
	v_pk_mul_f32 v[42:43], v[42:43], v[54:55] op_sel_hi:[1,0]
	v_pk_mul_f32 v[44:45], v[160:161], v[44:45]
	v_pk_mul_f32 v[46:47], v[162:163], v[46:47]
	v_cvt_pk_bf16_f32 v44, v44, v45
	v_cvt_pk_bf16_f32 v45, v46, v47
	global_store_dwordx2 v[52:53], v[44:45], off
	v_pk_mul_f32 v[36:37], v[36:37], v[54:55] op_sel_hi:[1,0]
	v_pk_mul_f32 v[38:39], v[38:39], v[54:55] op_sel_hi:[1,0]
	v_pk_mul_f32 v[32:33], v[32:33], v[54:55] op_sel_hi:[1,0]
	v_pk_mul_f32 v[34:35], v[34:35], v[54:55] op_sel_hi:[1,0]
	v_pk_mul_f32 v[40:41], v[166:167], v[40:41]
	v_pk_mul_f32 v[42:43], v[42:43], v[168:169]
	v_cvt_pk_bf16_f32 v40, v40, v41
	v_cvt_pk_bf16_f32 v41, v42, v43
	global_store_dwordx2 v[52:53], v[40:41], off offset:512
	v_pk_mul_f32 v[36:37], v[36:37], v[170:171]
	v_pk_mul_f32 v[38:39], v[38:39], v[172:173]
	v_cvt_pk_bf16_f32 v36, v36, v37
	v_cvt_pk_bf16_f32 v37, v38, v39
	global_store_dwordx2 v[52:53], v[36:37], off offset:1024
	v_pk_mul_f32 v[32:33], v[32:33], v[174:175]
	v_pk_mul_f32 v[34:35], v[34:35], v[176:177]
	v_cvt_pk_bf16_f32 v32, v32, v33
	v_cvt_pk_bf16_f32 v33, v34, v35
	global_store_dwordx2 v[52:53], v[32:33], off offset:1536
	s_or_b64 exec, exec, s[10:11]
	s_and_saveexec_b64 s[8:9], s[6:7]
	s_cbranch_execz .LBB0_96
.LBB0_98:
	v_mov_b32_e32 v36, v89
	v_mov_b32_e32 v186, v89
	s_nop 1
	v_permlane32_swap_b32_e32 v36, v186
	v_ashrrev_i32_e32 v97, 31, v96
	v_lshlrev_b32_e32 v38, 16, v107
	s_waitcnt lgkmcnt(0)
	v_add_f32_e32 v36, v36, v186
	v_mov_b32_e32 v37, v36
	v_mov_b32_e32 v187, v36
	s_nop 1
	v_permlane16_swap_b32_e32 v37, v187
	s_waitcnt lgkmcnt(0)
	v_add_f32_e32 v36, v37, v187
	s_nop 1
	v_mov_b32_dpp v37, v36 row_ror:8 row_mask:0xf bank_mask:0xf
	s_waitcnt lgkmcnt(0)
	v_add_f32_e32 v36, v36, v37
	s_nop 1
	v_mov_b32_dpp v37, v36 row_ror:4 row_mask:0xf bank_mask:0xa
	v_mov_b32_dpp v37, v36 row_ror:12 row_mask:0xf bank_mask:0x5
	s_waitcnt lgkmcnt(0)
	v_add_f32_e32 v36, v36, v37
	s_nop 1
	v_mov_b32_dpp v37, v36 quad_perm:[2,3,0,1] row_mask:0xf bank_mask:0xf
	s_waitcnt lgkmcnt(0)
	v_add_f32_e32 v39, v36, v37
	s_nop 1
	v_mov_b32_dpp v40, v39 quad_perm:[1,0,3,2] row_mask:0xf bank_mask:0xf
	v_lshlrev_b32_e32 v36, 16, v106
	v_and_b32_e32 v37, 0xffff0000, v106
	s_waitcnt lgkmcnt(0)
	v_add_f32_e32 v39, v39, v40
	v_fmamk_f32 v39, v39, 0x3a800000, v198
	v_mul_f32_e32 v40, 0x4b800000, v39
	v_cmp_gt_f32_e64 s[6:7], s51, v39
	s_nop 1
	v_cndmask_b32_e64 v39, v39, v40, s[6:7]
	v_rsq_f32_e32 v42, v39
	v_and_b32_e32 v39, 0xffff0000, v107
	v_lshlrev_b64 v[40:41], 12, v[96:97]
	v_lshl_add_u64 v[40:41], v[70:71], 0, v[40:41]
	v_mul_f32_e32 v43, 0x45800000, v42
	v_cndmask_b32_e64 v42, v42, v43, s[6:7]
	v_pk_mul_f32 v[36:37], v[42:43], v[36:37] op_sel_hi:[0,1]
	v_pk_mul_f32 v[38:39], v[42:43], v[38:39] op_sel_hi:[0,1]
	v_pk_fma_f32 v[28:29], v[142:143], v[36:37], v[28:29]
	v_pk_fma_f32 v[30:31], v[144:145], v[38:39], v[30:31]
	global_store_dwordx4 v[40:41], v[28:31], off
	v_lshlrev_b32_e32 v36, 16, v104
	v_and_b32_e32 v37, 0xffff0000, v104
	v_lshlrev_b32_e32 v38, 16, v105
	v_and_b32_e32 v39, 0xffff0000, v105
	v_pk_mul_f32 v[36:37], v[42:43], v[36:37] op_sel_hi:[0,1]
	v_pk_mul_f32 v[38:39], v[42:43], v[38:39] op_sel_hi:[0,1]
	v_pk_fma_f32 v[24:25], v[36:37], v[146:147], v[24:25]
	v_pk_fma_f32 v[26:27], v[38:39], v[148:149], v[26:27]
	global_store_dwordx4 v[40:41], v[24:27], off offset:1024
	v_lshlrev_b32_e32 v36, 16, v102
	v_and_b32_e32 v37, 0xffff0000, v102
	v_lshlrev_b32_e32 v38, 16, v103
	v_and_b32_e32 v39, 0xffff0000, v103
	v_pk_mul_f32 v[36:37], v[42:43], v[36:37] op_sel_hi:[0,1]
	v_pk_mul_f32 v[38:39], v[42:43], v[38:39] op_sel_hi:[0,1]
	v_pk_fma_f32 v[20:21], v[36:37], v[152:153], v[20:21]
	v_pk_fma_f32 v[22:23], v[38:39], v[154:155], v[22:23]
	global_store_dwordx4 v[40:41], v[20:23], off offset:2048
	v_lshlrev_b32_e32 v36, 16, v100
	v_and_b32_e32 v37, 0xffff0000, v100
	v_lshlrev_b32_e32 v38, 16, v101
	v_and_b32_e32 v39, 0xffff0000, v101
	v_pk_mul_f32 v[36:37], v[42:43], v[36:37] op_sel_hi:[0,1]
	v_pk_mul_f32 v[38:39], v[42:43], v[38:39] op_sel_hi:[0,1]
	v_mov_b32_e32 v42, v31
	v_mov_b32_e32 v43, v27
	v_pk_fma_f32 v[16:17], v[36:37], v[156:157], v[16:17]
	v_pk_fma_f32 v[18:19], v[38:39], v[158:159], v[18:19]
	global_store_dwordx4 v[40:41], v[16:19], off offset:3072
	v_mov_b32_e32 v38, v29
	v_mov_b32_e32 v39, v25
	v_mov_b32_e32 v36, v28
	v_mov_b32_e32 v37, v24
	v_pk_mul_f32 v[38:39], v[38:39], v[38:39]
	v_mov_b32_e32 v40, v30
	v_mov_b32_e32 v41, v26
	v_pk_fma_f32 v[36:37], v[36:37], v[36:37], v[38:39]
	v_mov_b32_e32 v38, v21
	v_pk_fma_f32 v[36:37], v[40:41], v[40:41], v[36:37]
	v_mov_b32_e32 v39, v17
	v_pk_fma_f32 v[36:37], v[42:43], v[42:43], v[36:37]
	v_pk_mul_f32 v[38:39], v[38:39], v[38:39]
	v_add_f32_e32 v44, v36, v37
	v_mov_b32_e32 v36, v20
	v_mov_b32_e32 v37, v16
	v_mov_b32_e32 v40, v22
	v_mov_b32_e32 v41, v18
	v_pk_fma_f32 v[36:37], v[36:37], v[36:37], v[38:39]
	v_mov_b32_e32 v42, v23
	v_mov_b32_e32 v43, v19
	v_pk_fma_f32 v[36:37], v[40:41], v[40:41], v[36:37]
	s_nop 0
	v_pk_fma_f32 v[36:37], v[42:43], v[42:43], v[36:37]
	s_nop 0
	v_add_f32_e32 v36, v44, v36
	v_add_f32_e32 v36, v36, v37
	v_mov_b32_e32 v37, v36
	v_mov_b32_e32 v188, v36
	s_nop 1
	v_permlane32_swap_b32_e32 v37, v188
	s_waitcnt lgkmcnt(0)
	v_add_f32_e32 v36, v37, v188
	v_mov_b32_e32 v37, v36
	v_mov_b32_e32 v189, v36
	s_nop 1
	v_permlane16_swap_b32_e32 v37, v189
	s_waitcnt lgkmcnt(0)
	v_add_f32_e32 v36, v37, v189
	s_nop 1
	v_mov_b32_dpp v37, v36 row_ror:8 row_mask:0xf bank_mask:0xf
	s_waitcnt lgkmcnt(0)
	v_add_f32_e32 v36, v36, v37
	s_nop 1
	v_mov_b32_dpp v37, v36 row_ror:4 row_mask:0xf bank_mask:0xa
	v_mov_b32_dpp v37, v36 row_ror:12 row_mask:0xf bank_mask:0x5
	s_waitcnt lgkmcnt(0)
	v_add_f32_e32 v36, v36, v37
	s_nop 1
	v_mov_b32_dpp v37, v36 quad_perm:[2,3,0,1] row_mask:0xf bank_mask:0xf
	s_waitcnt lgkmcnt(0)
	v_add_f32_e32 v36, v36, v37
	s_nop 1
	v_mov_b32_dpp v37, v36 quad_perm:[1,0,3,2] row_mask:0xf bank_mask:0xf
	s_waitcnt lgkmcnt(0)
	v_add_f32_e32 v36, v36, v37
	v_fmamk_f32 v36, v36, 0x3a800000, v198
	v_mul_f32_e32 v37, 0x4b800000, v36
	v_cmp_gt_f32_e64 s[6:7], s51, v36
	s_nop 1
	v_cndmask_b32_e64 v36, v36, v37, s[6:7]
	v_rsq_f32_e32 v38, v36
	v_lshlrev_b64 v[36:37], 11, v[96:97]
	v_lshl_add_u64 v[36:37], v[74:75], 0, v[36:37]
	v_mul_f32_e32 v39, 0x45800000, v38
	v_cndmask_b32_e64 v38, v38, v39, s[6:7]
	v_pk_mul_f32 v[28:29], v[28:29], v[38:39] op_sel_hi:[1,0]
	v_pk_mul_f32 v[30:31], v[30:31], v[38:39] op_sel_hi:[1,0]
	v_pk_mul_f32 v[24:25], v[24:25], v[38:39] op_sel_hi:[1,0]
	v_pk_mul_f32 v[26:27], v[26:27], v[38:39] op_sel_hi:[1,0]
	v_pk_mul_f32 v[28:29], v[160:161], v[28:29]
	v_pk_mul_f32 v[30:31], v[162:163], v[30:31]
	v_cvt_pk_bf16_f32 v28, v28, v29
	v_cvt_pk_bf16_f32 v29, v30, v31
	global_store_dwordx2 v[36:37], v[28:29], off
	v_pk_mul_f32 v[20:21], v[20:21], v[38:39] op_sel_hi:[1,0]
	v_pk_mul_f32 v[22:23], v[22:23], v[38:39] op_sel_hi:[1,0]
	v_pk_mul_f32 v[16:17], v[16:17], v[38:39] op_sel_hi:[1,0]
	v_pk_mul_f32 v[18:19], v[18:19], v[38:39] op_sel_hi:[1,0]
	v_pk_mul_f32 v[24:25], v[166:167], v[24:25]
	v_pk_mul_f32 v[26:27], v[26:27], v[168:169]
	v_cvt_pk_bf16_f32 v24, v24, v25
	v_cvt_pk_bf16_f32 v25, v26, v27
	global_store_dwordx2 v[36:37], v[24:25], off offset:512
	v_pk_mul_f32 v[20:21], v[20:21], v[170:171]
	v_pk_mul_f32 v[22:23], v[22:23], v[172:173]
	v_cvt_pk_bf16_f32 v20, v20, v21
	v_cvt_pk_bf16_f32 v21, v22, v23
	global_store_dwordx2 v[36:37], v[20:21], off offset:1024
	v_pk_mul_f32 v[16:17], v[16:17], v[174:175]
	v_pk_mul_f32 v[18:19], v[18:19], v[176:177]
	v_cvt_pk_bf16_f32 v16, v16, v17
	v_cvt_pk_bf16_f32 v17, v18, v19
	global_store_dwordx2 v[36:37], v[16:17], off offset:1536
	s_or_b64 exec, exec, s[8:9]
	s_and_saveexec_b64 s[6:7], s[4:5]
	s_cbranch_execz .LBB0_85
.LBB0_99:
	s_waitcnt vmcnt(0)
	v_mov_b32_e32 v20, v65
	v_mov_b32_e32 v184, v65
	s_nop 1
	v_permlane32_swap_b32_e32 v20, v184
	v_ashrrev_i32_e32 v89, 31, v88
	v_lshlrev_b32_e32 v22, 16, v99
	s_waitcnt lgkmcnt(0)
	v_add_f32_e32 v20, v20, v184
	v_mov_b32_e32 v21, v20
	v_mov_b32_e32 v185, v20
	s_nop 1
	v_permlane16_swap_b32_e32 v21, v185
	s_waitcnt lgkmcnt(0)
	v_add_f32_e32 v20, v21, v185
	s_nop 1
	v_mov_b32_dpp v21, v20 row_ror:8 row_mask:0xf bank_mask:0xf
	s_waitcnt lgkmcnt(0)
	v_add_f32_e32 v20, v20, v21
	s_nop 1
	v_mov_b32_dpp v21, v20 row_ror:4 row_mask:0xf bank_mask:0xa
	v_mov_b32_dpp v21, v20 row_ror:12 row_mask:0xf bank_mask:0x5
	s_waitcnt lgkmcnt(0)
	v_add_f32_e32 v20, v20, v21
	s_nop 1
	v_mov_b32_dpp v21, v20 quad_perm:[2,3,0,1] row_mask:0xf bank_mask:0xf
	s_waitcnt lgkmcnt(0)
	v_add_f32_e32 v23, v20, v21
	s_nop 1
	v_mov_b32_dpp v24, v23 quad_perm:[1,0,3,2] row_mask:0xf bank_mask:0xf
	v_lshlrev_b32_e32 v20, 16, v98
	v_and_b32_e32 v21, 0xffff0000, v98
	s_waitcnt lgkmcnt(0)
	v_add_f32_e32 v23, v23, v24
	v_fmamk_f32 v23, v23, 0x3a800000, v198
	v_mul_f32_e32 v24, 0x4b800000, v23
	v_cmp_gt_f32_e64 s[4:5], s51, v23
	s_nop 1
	v_cndmask_b32_e64 v23, v23, v24, s[4:5]
	v_rsq_f32_e32 v26, v23
	v_and_b32_e32 v23, 0xffff0000, v99
	v_lshlrev_b64 v[24:25], 12, v[88:89]
	v_lshl_add_u64 v[24:25], v[70:71], 0, v[24:25]
	v_mul_f32_e32 v27, 0x45800000, v26
	v_cndmask_b32_e64 v26, v26, v27, s[4:5]
	v_pk_mul_f32 v[20:21], v[26:27], v[20:21] op_sel_hi:[0,1]
	v_pk_mul_f32 v[22:23], v[26:27], v[22:23] op_sel_hi:[0,1]
	v_pk_fma_f32 v[12:13], v[142:143], v[20:21], v[12:13]
	v_pk_fma_f32 v[14:15], v[144:145], v[22:23], v[14:15]
	global_store_dwordx4 v[24:25], v[12:15], off
	v_lshlrev_b32_e32 v20, 16, v94
	v_and_b32_e32 v21, 0xffff0000, v94
	v_lshlrev_b32_e32 v22, 16, v95
	v_and_b32_e32 v23, 0xffff0000, v95
	v_pk_mul_f32 v[20:21], v[26:27], v[20:21] op_sel_hi:[0,1]
	v_pk_mul_f32 v[22:23], v[26:27], v[22:23] op_sel_hi:[0,1]
	v_pk_fma_f32 v[8:9], v[20:21], v[146:147], v[8:9]
	v_pk_fma_f32 v[10:11], v[22:23], v[148:149], v[10:11]
	global_store_dwordx4 v[24:25], v[8:11], off offset:1024
	v_lshlrev_b32_e32 v20, 16, v92
	v_and_b32_e32 v21, 0xffff0000, v92
	v_lshlrev_b32_e32 v22, 16, v93
	v_and_b32_e32 v23, 0xffff0000, v93
	v_pk_mul_f32 v[20:21], v[26:27], v[20:21] op_sel_hi:[0,1]
	v_pk_mul_f32 v[22:23], v[26:27], v[22:23] op_sel_hi:[0,1]
	v_pk_fma_f32 v[4:5], v[20:21], v[152:153], v[4:5]
	v_pk_fma_f32 v[6:7], v[22:23], v[154:155], v[6:7]
	global_store_dwordx4 v[24:25], v[4:7], off offset:2048
	v_lshlrev_b32_e32 v20, 16, v90
	v_and_b32_e32 v21, 0xffff0000, v90
	v_lshlrev_b32_e32 v22, 16, v91
	v_and_b32_e32 v23, 0xffff0000, v91
	v_pk_mul_f32 v[20:21], v[26:27], v[20:21] op_sel_hi:[0,1]
	v_pk_mul_f32 v[22:23], v[26:27], v[22:23] op_sel_hi:[0,1]
	v_mov_b32_e32 v26, v15
	v_mov_b32_e32 v27, v11
	v_pk_fma_f32 v[0:1], v[20:21], v[156:157], v[0:1]
	v_pk_fma_f32 v[2:3], v[22:23], v[158:159], v[2:3]
	global_store_dwordx4 v[24:25], v[0:3], off offset:3072
	v_mov_b32_e32 v22, v13
	v_mov_b32_e32 v23, v9
	v_mov_b32_e32 v20, v12
	v_mov_b32_e32 v21, v8
	v_pk_mul_f32 v[22:23], v[22:23], v[22:23]
	v_mov_b32_e32 v24, v14
	v_mov_b32_e32 v25, v10
	v_pk_fma_f32 v[20:21], v[20:21], v[20:21], v[22:23]
	v_mov_b32_e32 v22, v5
	v_pk_fma_f32 v[20:21], v[24:25], v[24:25], v[20:21]
	v_mov_b32_e32 v23, v1
	v_pk_fma_f32 v[20:21], v[26:27], v[26:27], v[20:21]
	v_pk_mul_f32 v[22:23], v[22:23], v[22:23]
	v_add_f32_e32 v28, v20, v21
	v_mov_b32_e32 v20, v4
	v_mov_b32_e32 v21, v0
	v_mov_b32_e32 v24, v6
	v_mov_b32_e32 v25, v2
	v_pk_fma_f32 v[20:21], v[20:21], v[20:21], v[22:23]
	v_mov_b32_e32 v26, v7
	v_mov_b32_e32 v27, v3
	v_pk_fma_f32 v[20:21], v[24:25], v[24:25], v[20:21]
	s_nop 0
	v_pk_fma_f32 v[20:21], v[26:27], v[26:27], v[20:21]
	s_nop 0
	v_add_f32_e32 v20, v28, v20
	v_add_f32_e32 v20, v20, v21
	v_mov_b32_e32 v21, v20
	v_mov_b32_e32 v186, v20
	s_nop 1
	v_permlane32_swap_b32_e32 v21, v186
	s_waitcnt lgkmcnt(0)
	v_add_f32_e32 v20, v21, v186
	v_mov_b32_e32 v21, v20
	v_mov_b32_e32 v187, v20
	s_nop 1
	v_permlane16_swap_b32_e32 v21, v187
	s_waitcnt lgkmcnt(0)
	v_add_f32_e32 v20, v21, v187
	s_nop 1
	v_mov_b32_dpp v21, v20 row_ror:8 row_mask:0xf bank_mask:0xf
	s_waitcnt lgkmcnt(0)
	v_add_f32_e32 v20, v20, v21
	s_nop 1
	v_mov_b32_dpp v21, v20 row_ror:4 row_mask:0xf bank_mask:0xa
	v_mov_b32_dpp v21, v20 row_ror:12 row_mask:0xf bank_mask:0x5
	s_waitcnt lgkmcnt(0)
	v_add_f32_e32 v20, v20, v21
	s_nop 1
	v_mov_b32_dpp v21, v20 quad_perm:[2,3,0,1] row_mask:0xf bank_mask:0xf
	s_waitcnt lgkmcnt(0)
	v_add_f32_e32 v20, v20, v21
	s_nop 1
	v_mov_b32_dpp v21, v20 quad_perm:[1,0,3,2] row_mask:0xf bank_mask:0xf
	s_waitcnt lgkmcnt(0)
	v_add_f32_e32 v20, v20, v21
	v_fmamk_f32 v20, v20, 0x3a800000, v198
	v_mul_f32_e32 v21, 0x4b800000, v20
	v_cmp_gt_f32_e64 s[4:5], s51, v20
	s_nop 1
	v_cndmask_b32_e64 v20, v20, v21, s[4:5]
	v_rsq_f32_e32 v22, v20
	v_lshlrev_b64 v[20:21], 11, v[88:89]
	v_lshl_add_u64 v[20:21], v[74:75], 0, v[20:21]
	v_mul_f32_e32 v23, 0x45800000, v22
	v_cndmask_b32_e64 v22, v22, v23, s[4:5]
	v_pk_mul_f32 v[12:13], v[12:13], v[22:23] op_sel_hi:[1,0]
	v_pk_mul_f32 v[14:15], v[14:15], v[22:23] op_sel_hi:[1,0]
	v_pk_mul_f32 v[8:9], v[8:9], v[22:23] op_sel_hi:[1,0]
	v_pk_mul_f32 v[10:11], v[10:11], v[22:23] op_sel_hi:[1,0]
	v_pk_mul_f32 v[12:13], v[160:161], v[12:13]
	v_pk_mul_f32 v[14:15], v[162:163], v[14:15]
	v_cvt_pk_bf16_f32 v12, v12, v13
	v_cvt_pk_bf16_f32 v13, v14, v15
	global_store_dwordx2 v[20:21], v[12:13], off
	v_pk_mul_f32 v[4:5], v[4:5], v[22:23] op_sel_hi:[1,0]
	v_pk_mul_f32 v[6:7], v[6:7], v[22:23] op_sel_hi:[1,0]
	v_pk_mul_f32 v[0:1], v[0:1], v[22:23] op_sel_hi:[1,0]
	v_pk_mul_f32 v[2:3], v[2:3], v[22:23] op_sel_hi:[1,0]
	v_pk_mul_f32 v[8:9], v[166:167], v[8:9]
	v_pk_mul_f32 v[10:11], v[10:11], v[168:169]
	v_cvt_pk_bf16_f32 v8, v8, v9
	v_cvt_pk_bf16_f32 v9, v10, v11
	global_store_dwordx2 v[20:21], v[8:9], off offset:512
	v_pk_mul_f32 v[4:5], v[4:5], v[170:171]
	v_pk_mul_f32 v[6:7], v[6:7], v[172:173]
	v_cvt_pk_bf16_f32 v4, v4, v5
	v_cvt_pk_bf16_f32 v5, v6, v7
	global_store_dwordx2 v[20:21], v[4:5], off offset:1024
	v_pk_mul_f32 v[0:1], v[0:1], v[174:175]
	v_pk_mul_f32 v[2:3], v[2:3], v[176:177]
	v_cvt_pk_bf16_f32 v0, v0, v1
	v_cvt_pk_bf16_f32 v1, v2, v3
	global_store_dwordx2 v[20:21], v[0:1], off offset:1536
	s_branch .LBB0_85

.LBB0_527:
	v_readlane_b32 s4, v249, 27
	v_add_u32_e32 v2, 0xffffc000, v63
	v_lshl_add_u64 v[0:1], v[50:51], 0, s[12:13]
	v_cmp_gt_i32_e32 vcc, s33, v63
	v_readlane_b32 s5, v249, 28
	v_readlane_b32 s6, v249, 29
	v_readlane_b32 s7, v249, 30
	v_cndmask_b32_e32 v1, 0, v1, vcc
	v_cndmask_b32_e32 v0, v2, v0, vcc
	v_mov_b32_e32 v36, s7
	v_mov_b32_e32 v37, s5
	v_mov_b32_e32 v38, s6
	v_mov_b32_e32 v39, s4
	v_cndmask_b32_e32 v3, v36, v37, vcc
	v_cndmask_b32_e32 v2, v38, v39, vcc
	v_lshlrev_b64 v[4:5], 12, v[0:1]
	v_lshl_add_u64 v[2:3], v[2:3], 0, v[4:5]
	v_mov_b32_e32 v55, v197
	v_lshl_add_u64 v[2:3], v[2:3], 0, v[54:55]
	global_load_dwordx4 v[28:31], v[2:3], off nt
	global_load_dwordx4 v[24:27], v[2:3], off offset:1024 nt
	global_load_dwordx4 v[20:23], v[2:3], off offset:2048 nt
	global_load_dwordx4 v[16:19], v[2:3], off offset:3072 nt
	v_readlane_b32 s4, v249, 21
	v_readlane_b32 s6, v249, 25
	v_readlane_b32 s5, v249, 22
	v_readlane_b32 s7, v249, 26
	v_mov_b32_e32 v4, s4
	v_mov_b32_e32 v2, s5
	v_mov_b32_e32 v3, s7
	v_mov_b32_e32 v5, s6
	v_lshlrev_b32_e32 v196, 4, v48
	v_cndmask_b32_e32 v3, v2, v3, vcc
	v_cndmask_b32_e32 v2, v4, v5, vcc
	s_waitcnt vmcnt(0)
	v_lshl_add_u64 v[70:71], v[2:3], 0, v[196:197]
	global_load_dwordx4 v[66:69], v[70:71], off
	v_readlane_b32 s16, v250, 53
	v_readlane_b32 s23, v250, 60
	v_mov_b32_e32 v6, s57
	v_readlane_b32 s22, v250, 59
	v_mov_b32_e32 v7, s23
	v_cndmask_b32_e32 v5, v6, v7, vcc
	v_mov_b32_e32 v8, s56
	v_mov_b32_e32 v9, s22
	v_cndmask_b32_e32 v4, v8, v9, vcc
	v_add_u32_e32 v65, s0, v63
	s_movk_i32 s6, 0x4800
	v_add_u32_e32 v64, s2, v63
	v_cmp_gt_i32_e64 s[4:5], s6, v65
	v_cmp_gt_i32_e32 vcc, s6, v64
	v_lshlrev_b64 v[0:1], 11, v[0:1]
	v_cndmask_b32_e64 v40, v63, v65, s[4:5]
	v_cndmask_b32_e32 v41, v63, v64, vcc
	v_ashrrev_i32_e32 v42, 31, v40
	v_cmp_gt_i32_e64 s[6:7], s33, v40
	v_lshl_add_u64 v[0:1], v[4:5], 0, v[0:1]
	v_lshlrev_b32_e32 v56, 3, v48
	v_cndmask_b32_e64 v5, v36, v37, s[6:7]
	v_cndmask_b32_e64 v4, v38, v39, s[6:7]
	v_mov_b32_e32 v57, v197
	v_lshl_add_u64 v[72:73], v[0:1], 0, v[56:57]
	v_readlane_b32 s17, v250, 54
	v_readlane_b32 s18, v250, 55
	v_readlane_b32 s19, v250, 56
	v_readlane_b32 s20, v250, 57
	v_readlane_b32 s21, v250, 58
	v_readlane_b32 s24, v250, 61
	v_readlane_b32 s25, v250, 62
	v_readlane_b32 s26, v250, 63
	v_readlane_b32 s27, v249, 0
	v_readlane_b32 s28, v249, 1
	v_readlane_b32 s29, v249, 2
	v_readlane_b32 s30, v249, 3
	v_readlane_b32 s31, v249, 4
	v_mov_b32_e32 v6, v29
	v_mov_b32_e32 v7, v25
	v_mov_b32_e32 v2, v28
	v_mov_b32_e32 v3, v24
	v_mov_b32_e32 v14, v21
	v_mov_b32_e32 v15, v17
	v_pk_mul_f32 v[6:7], v[6:7], v[6:7]
	v_mov_b32_e32 v8, v30
	v_mov_b32_e32 v9, v26
	v_mov_b32_e32 v12, v20
	v_mov_b32_e32 v13, v16
	v_pk_mul_f32 v[14:15], v[14:15], v[14:15]
	v_pk_fma_f32 v[2:3], v[2:3], v[2:3], v[6:7]
	v_mov_b32_e32 v10, v31
	v_mov_b32_e32 v11, v27
	v_mov_b32_e32 v32, v22
	v_mov_b32_e32 v33, v18
	v_pk_fma_f32 v[6:7], v[12:13], v[12:13], v[14:15]
	v_pk_fma_f32 v[2:3], v[8:9], v[8:9], v[2:3]
	v_mov_b32_e32 v34, v23
	v_mov_b32_e32 v35, v19
	v_pk_fma_f32 v[6:7], v[32:33], v[32:33], v[6:7]
	v_pk_fma_f32 v[2:3], v[10:11], v[10:11], v[2:3]
	v_pk_fma_f32 v[6:7], v[34:35], v[34:35], v[6:7]
	v_add_f32_e32 v2, v2, v3
	v_add_f32_e32 v2, v2, v6
	v_add_f32_e32 v2, v2, v7
	v_mov_b32_e32 v3, v2
	v_mov_b32_e32 v184, v2
	s_nop 1
	v_permlane32_swap_b32_e32 v3, v184
	v_add_u32_e32 v6, 0xffffc000, v40
	v_ashrrev_i32_e32 v7, 31, v41
	v_add_u32_e32 v8, 0xffffc000, v41
	s_waitcnt lgkmcnt(0)
	v_add_f32_e32 v9, v3, v184
	v_mov_b32_e32 v10, v9
	v_mov_b32_e32 v185, v9
	s_nop 1
	v_permlane16_swap_b32_e32 v10, v185
	v_cndmask_b32_e64 v3, 0, v42, s[6:7]
	v_cndmask_b32_e64 v2, v6, v40, s[6:7]
	v_cmp_gt_i32_e64 s[6:7], s33, v41
	v_lshlrev_b64 v[0:1], 12, v[2:3]
	s_waitcnt lgkmcnt(0)
	v_add_f32_e32 v10, v10, v185
	s_nop 1
	v_mov_b32_dpp v11, v10 row_ror:8 row_mask:0xf bank_mask:0xf
	v_cndmask_b32_e64 v7, 0, v7, s[6:7]
	v_cndmask_b32_e64 v6, v8, v41, s[6:7]
	v_lshlrev_b64 v[2:3], 12, v[6:7]
	v_lshl_add_u64 v[0:1], v[4:5], 0, v[0:1]
	s_waitcnt lgkmcnt(0)
	v_add_f32_e32 v10, v10, v11
	s_nop 1
	v_mov_b32_dpp v11, v10 row_ror:4 row_mask:0xf bank_mask:0xa
	v_mov_b32_dpp v11, v10 row_ror:12 row_mask:0xf bank_mask:0x5
	v_lshl_add_u64 v[0:1], v[0:1], 0, v[54:55]
	v_cndmask_b32_e64 v9, v36, v37, s[6:7]
	v_cndmask_b32_e64 v8, v38, v39, s[6:7]
	global_load_dwordx4 v[44:47], v[0:1], off nt
	global_load_dwordx4 v[40:43], v[0:1], off offset:1024 nt
	global_load_dwordx4 v[36:39], v[0:1], off offset:2048 nt
	global_load_dwordx4 v[32:35], v[0:1], off offset:3072 nt
	s_waitcnt lgkmcnt(0)
	v_add_f32_e32 v6, v10, v11
	s_nop 1
	v_mov_b32_dpp v7, v6 quad_perm:[2,3,0,1] row_mask:0xf bank_mask:0xf
	v_lshl_add_u64 v[2:3], v[8:9], 0, v[2:3]
	v_lshl_add_u64 v[2:3], v[2:3], 0, v[54:55]
	s_waitcnt lgkmcnt(0)
	v_add_f32_e32 v4, v6, v7
	s_nop 1
	v_mov_b32_dpp v5, v4 quad_perm:[1,0,3,2] row_mask:0xf bank_mask:0xf
	s_waitcnt lgkmcnt(0)
	v_add_f32_e32 v0, v4, v5
	v_fmamk_f32 v0, v0, 0x3a800000, v198
	v_mul_f32_e32 v1, 0x4b800000, v0
	v_cmp_gt_f32_e64 s[6:7], s51, v0
	s_nop 1
	v_cndmask_b32_e64 v0, v0, v1, s[6:7]
	v_rsq_f32_e32 v55, v0
	global_load_dwordx4 v[12:15], v[2:3], off nt
	global_load_dwordx4 v[8:11], v[2:3], off offset:1024 nt
	global_load_dwordx4 v[4:7], v[2:3], off offset:2048 nt
	s_nop 0
	global_load_dwordx4 v[0:3], v[2:3], off offset:3072 nt
	v_mul_f32_e32 v74, 0x45800000, v55
	v_cndmask_b32_e64 v74, v55, v74, s[6:7]
	v_pk_mul_f32 v[28:29], v[28:29], v[74:75] op_sel_hi:[1,0]
	v_pk_mul_f32 v[30:31], v[30:31], v[74:75] op_sel_hi:[1,0]
	s_waitcnt vmcnt(8)
	v_pk_mul_f32 v[28:29], v[66:67], v[28:29]
	v_pk_mul_f32 v[30:31], v[68:69], v[30:31]
	v_cvt_pk_bf16_f32 v28, v28, v29
	v_cvt_pk_bf16_f32 v29, v30, v31
	global_store_dwordx2 v[72:73], v[28:29], off
	global_load_dwordx4 v[28:31], v[70:71], off offset:1024
	v_pk_mul_f32 v[24:25], v[24:25], v[74:75] op_sel_hi:[1,0]
	v_pk_mul_f32 v[26:27], v[26:27], v[74:75] op_sel_hi:[1,0]
	v_pk_mul_f32 v[20:21], v[20:21], v[74:75] op_sel_hi:[1,0]
	v_pk_mul_f32 v[22:23], v[22:23], v[74:75] op_sel_hi:[1,0]
	v_pk_mul_f32 v[16:17], v[16:17], v[74:75] op_sel_hi:[1,0]
	v_pk_mul_f32 v[18:19], v[18:19], v[74:75] op_sel_hi:[1,0]
	s_waitcnt vmcnt(0)
	v_pk_mul_f32 v[24:25], v[28:29], v[24:25]
	v_pk_mul_f32 v[26:27], v[30:31], v[26:27]
	v_cvt_pk_bf16_f32 v24, v24, v25
	v_cvt_pk_bf16_f32 v25, v26, v27
	global_store_dwordx2 v[72:73], v[24:25], off offset:512
	global_load_dwordx4 v[24:27], v[70:71], off offset:2048
	s_waitcnt vmcnt(0)
	v_pk_mul_f32 v[20:21], v[20:21], v[24:25]
	v_pk_mul_f32 v[22:23], v[22:23], v[26:27]
	v_cvt_pk_bf16_f32 v20, v20, v21
	v_cvt_pk_bf16_f32 v21, v22, v23
	global_store_dwordx2 v[72:73], v[20:21], off offset:1024
	global_load_dwordx4 v[20:23], v[70:71], off offset:3072
	s_waitcnt vmcnt(0)
	v_pk_mul_f32 v[16:17], v[16:17], v[20:21]
	v_pk_mul_f32 v[18:19], v[18:19], v[22:23]
	v_cvt_pk_bf16_f32 v16, v16, v17
	v_cvt_pk_bf16_f32 v17, v18, v19
	global_store_dwordx2 v[72:73], v[16:17], off offset:1536
	s_and_saveexec_b64 s[6:7], s[4:5]
	s_cbranch_execz .LBB0_529
	v_readlane_b32 s16, v249, 21
	v_readlane_b32 s18, v249, 25
	v_readlane_b32 s17, v249, 22
	v_readlane_b32 s19, v249, 26
	v_cmp_gt_i32_e64 s[4:5], s33, v65
	v_mov_b32_e32 v16, s17
	v_mov_b32_e32 v17, s19
	v_cndmask_b32_e64 v17, v16, v17, s[4:5]
	v_mov_b32_e32 v16, s16
	v_mov_b32_e32 v18, s18
	v_cndmask_b32_e64 v16, v16, v18, s[4:5]
	v_lshl_add_u64 v[20:21], v[16:17], 0, v[196:197]
	global_load_dwordx4 v[16:19], v[20:21], off
	v_mov_b32_e32 v24, v45
	v_mov_b32_e32 v25, v41
	v_mov_b32_e32 v22, v44
	v_mov_b32_e32 v23, v40
	v_pk_mul_f32 v[24:25], v[24:25], v[24:25]
	v_mov_b32_e32 v26, v37
	v_pk_fma_f32 v[22:23], v[22:23], v[22:23], v[24:25]
	v_mov_b32_e32 v24, v46
	v_mov_b32_e32 v25, v42
	v_pk_fma_f32 v[22:23], v[24:25], v[24:25], v[22:23]
	v_mov_b32_e32 v24, v47
	v_mov_b32_e32 v25, v43
	v_mov_b32_e32 v27, v33
	v_pk_fma_f32 v[22:23], v[24:25], v[24:25], v[22:23]
	v_mov_b32_e32 v24, v36
	v_mov_b32_e32 v25, v32
	v_pk_mul_f32 v[26:27], v[26:27], v[26:27]
	v_add_f32_e32 v22, v22, v23
	v_pk_fma_f32 v[24:25], v[24:25], v[24:25], v[26:27]
	v_mov_b32_e32 v26, v38
	v_mov_b32_e32 v27, v34
	v_pk_fma_f32 v[24:25], v[26:27], v[26:27], v[24:25]
	v_mov_b32_e32 v26, v39
	v_mov_b32_e32 v27, v35
	v_pk_fma_f32 v[24:25], v[26:27], v[26:27], v[24:25]
	v_add_u32_e32 v26, 0xffffc000, v65
	v_add_f32_e32 v22, v22, v24
	v_add_f32_e32 v22, v22, v25
	v_mov_b32_e32 v23, v22
	v_mov_b32_e32 v186, v22
	s_nop 1
	v_permlane32_swap_b32_e32 v23, v186
	v_readlane_b32 s16, v250, 53
	v_readlane_b32 s22, v250, 59
	v_readlane_b32 s23, v250, 60
	v_mov_b32_e32 v27, s57
	s_waitcnt lgkmcnt(0)
	v_add_f32_e32 v22, v23, v186
	v_mov_b32_e32 v23, v22
	v_mov_b32_e32 v187, v22
	s_nop 1
	v_permlane16_swap_b32_e32 v23, v187
	v_mov_b32_e32 v28, s23
	v_mov_b32_e32 v29, s56
	v_mov_b32_e32 v30, s22
	v_readlane_b32 s17, v250, 54
	s_waitcnt lgkmcnt(0)
	v_add_f32_e32 v22, v23, v187
	s_nop 1
	v_mov_b32_dpp v23, v22 row_ror:8 row_mask:0xf bank_mask:0xf
	v_readlane_b32 s18, v250, 55
	v_readlane_b32 s19, v250, 56
	v_readlane_b32 s20, v250, 57
	v_readlane_b32 s21, v250, 58
	s_waitcnt lgkmcnt(0)
	v_add_f32_e32 v24, v22, v23
	s_nop 1
	v_mov_b32_dpp v25, v24 row_ror:4 row_mask:0xf bank_mask:0xa
	v_mov_b32_dpp v25, v24 row_ror:12 row_mask:0xf bank_mask:0x5
	v_lshl_add_u64 v[22:23], v[52:53], 0, s[12:13]
	v_cndmask_b32_e64 v22, v26, v22, s[4:5]
	v_cndmask_b32_e64 v23, 0, v23, s[4:5]
	v_lshlrev_b64 v[22:23], 11, v[22:23]
	s_waitcnt lgkmcnt(0)
	v_add_f32_e32 v24, v24, v25
	s_nop 1
	v_mov_b32_dpp v25, v24 quad_perm:[2,3,0,1] row_mask:0xf bank_mask:0xf
	v_readlane_b32 s24, v250, 61
	v_readlane_b32 s25, v250, 62
	v_readlane_b32 s26, v250, 63
	v_readlane_b32 s27, v249, 0
	s_waitcnt lgkmcnt(0)
	v_add_f32_e32 v31, v24, v25
	s_nop 1
	v_mov_b32_dpp v55, v31 quad_perm:[1,0,3,2] row_mask:0xf bank_mask:0xf
	v_cndmask_b32_e64 v25, v27, v28, s[4:5]
	v_cndmask_b32_e64 v24, v29, v30, s[4:5]
	v_lshl_add_u64 v[22:23], v[24:25], 0, v[22:23]
	v_lshl_add_u64 v[22:23], v[22:23], 0, v[56:57]
	s_waitcnt lgkmcnt(0)
	v_add_f32_e32 v26, v31, v55
	v_fmamk_f32 v26, v26, 0x3a800000, v198
	v_mul_f32_e32 v27, 0x4b800000, v26
	v_cmp_gt_f32_e64 s[4:5], s51, v26
	v_readlane_b32 s28, v249, 1
	v_readlane_b32 s29, v249, 2
	v_cndmask_b32_e64 v26, v26, v27, s[4:5]
	v_rsq_f32_e32 v26, v26
	v_readlane_b32 s30, v249, 3
	v_readlane_b32 s31, v249, 4
	v_mul_f32_e32 v24, 0x45800000, v26
	v_cndmask_b32_e64 v24, v26, v24, s[4:5]
	v_pk_mul_f32 v[26:27], v[44:45], v[24:25] op_sel_hi:[1,0]
	v_pk_mul_f32 v[28:29], v[46:47], v[24:25] op_sel_hi:[1,0]
	s_waitcnt vmcnt(0)
	v_pk_mul_f32 v[16:17], v[16:17], v[26:27]
	v_pk_mul_f32 v[18:19], v[18:19], v[28:29]
	v_cvt_pk_bf16_f32 v16, v16, v17
	v_cvt_pk_bf16_f32 v17, v18, v19
	global_store_dwordx2 v[22:23], v[16:17], off
	global_load_dwordx4 v[16:19], v[20:21], off offset:1024
	v_pk_mul_f32 v[26:27], v[40:41], v[24:25] op_sel_hi:[1,0]
	v_pk_mul_f32 v[28:29], v[42:43], v[24:25] op_sel_hi:[1,0]
	s_waitcnt vmcnt(0)
	v_pk_mul_f32 v[16:17], v[16:17], v[26:27]
	v_pk_mul_f32 v[18:19], v[18:19], v[28:29]
	v_cvt_pk_bf16_f32 v16, v16, v17
	v_cvt_pk_bf16_f32 v17, v18, v19
	global_store_dwordx2 v[22:23], v[16:17], off offset:512
	global_load_dwordx4 v[16:19], v[20:21], off offset:2048
	v_pk_mul_f32 v[26:27], v[36:37], v[24:25] op_sel_hi:[1,0]
	v_pk_mul_f32 v[28:29], v[38:39], v[24:25] op_sel_hi:[1,0]
	s_waitcnt vmcnt(0)
	v_pk_mul_f32 v[16:17], v[26:27], v[16:17]
	v_pk_mul_f32 v[18:19], v[28:29], v[18:19]
	v_cvt_pk_bf16_f32 v16, v16, v17
	v_cvt_pk_bf16_f32 v17, v18, v19
	global_store_dwordx2 v[22:23], v[16:17], off offset:1024
	global_load_dwordx4 v[16:19], v[20:21], off offset:3072
	v_pk_mul_f32 v[20:21], v[32:33], v[24:25] op_sel_hi:[1,0]
	v_pk_mul_f32 v[24:25], v[34:35], v[24:25] op_sel_hi:[1,0]
	s_waitcnt vmcnt(0)
	v_pk_mul_f32 v[16:17], v[20:21], v[16:17]
	v_pk_mul_f32 v[18:19], v[24:25], v[18:19]
	v_cvt_pk_bf16_f32 v16, v16, v17
	v_cvt_pk_bf16_f32 v17, v18, v19
	global_store_dwordx2 v[22:23], v[16:17], off offset:1536
.LBB0_529:
	s_or_b64 exec, exec, s[6:7]
	s_and_saveexec_b64 s[4:5], vcc
	s_cbranch_execz .LBB0_526
	v_readlane_b32 s6, v249, 21
	v_readlane_b32 s16, v249, 25
	v_readlane_b32 s7, v249, 22
	v_readlane_b32 s17, v249, 26
	v_cmp_gt_i32_e32 vcc, s33, v64
	v_mov_b32_e32 v16, s7
	v_mov_b32_e32 v17, s17
	v_cndmask_b32_e32 v17, v16, v17, vcc
	v_mov_b32_e32 v16, s6
	v_mov_b32_e32 v18, s16
	v_cndmask_b32_e32 v16, v16, v18, vcc
	v_lshl_add_u64 v[20:21], v[16:17], 0, v[196:197]
	global_load_dwordx4 v[16:19], v[20:21], off
	v_mov_b32_e32 v24, v13
	v_mov_b32_e32 v25, v9
	v_mov_b32_e32 v22, v12
	v_mov_b32_e32 v23, v8
	v_pk_mul_f32 v[24:25], v[24:25], v[24:25]
	v_mov_b32_e32 v26, v14
	v_mov_b32_e32 v27, v10
	v_pk_fma_f32 v[22:23], v[22:23], v[22:23], v[24:25]
	v_mov_b32_e32 v28, v15
	v_pk_fma_f32 v[22:23], v[26:27], v[26:27], v[22:23]
	v_mov_b32_e32 v26, v5
	v_mov_b32_e32 v27, v1
	v_mov_b32_e32 v29, v11
	v_mov_b32_e32 v24, v4
	v_mov_b32_e32 v25, v0
	v_pk_mul_f32 v[26:27], v[26:27], v[26:27]
	v_pk_fma_f32 v[22:23], v[28:29], v[28:29], v[22:23]
	v_mov_b32_e32 v28, v6
	v_mov_b32_e32 v29, v2
	v_pk_fma_f32 v[24:25], v[24:25], v[24:25], v[26:27]
	v_mov_b32_e32 v30, v7
	v_mov_b32_e32 v31, v3
	v_pk_fma_f32 v[24:25], v[28:29], v[28:29], v[24:25]
	v_add_f32_e32 v22, v22, v23
	v_pk_fma_f32 v[24:25], v[30:31], v[30:31], v[24:25]
	v_readlane_b32 s16, v250, 53
	v_add_f32_e32 v22, v22, v24
	v_add_f32_e32 v22, v22, v25
	v_mov_b32_e32 v23, v22
	v_mov_b32_e32 v188, v22
	s_nop 1
	v_permlane32_swap_b32_e32 v23, v188
	v_readlane_b32 s23, v250, 60
	v_add_u32_e32 v25, 0xffffc000, v64
	v_mov_b32_e32 v26, s57
	v_mov_b32_e32 v27, s23
	s_waitcnt lgkmcnt(0)
	v_add_f32_e32 v22, v23, v188
	v_mov_b32_e32 v23, v22
	v_mov_b32_e32 v189, v22
	s_nop 1
	v_permlane16_swap_b32_e32 v23, v189
	v_readlane_b32 s22, v250, 59
	v_ashrrev_i32_e32 v24, 31, v64
	v_mov_b32_e32 v28, s56
	v_mov_b32_e32 v29, s22
	s_waitcnt lgkmcnt(0)
	v_add_f32_e32 v22, v23, v189
	s_nop 1
	v_mov_b32_dpp v23, v22 row_ror:8 row_mask:0xf bank_mask:0xf
	v_mov_b32_e32 v57, v197
	v_readlane_b32 s17, v250, 54
	v_readlane_b32 s18, v250, 55
	v_readlane_b32 s19, v250, 56
	s_waitcnt lgkmcnt(0)
	v_add_f32_e32 v22, v22, v23
	s_nop 1
	v_mov_b32_dpp v23, v22 row_ror:4 row_mask:0xf bank_mask:0xa
	v_mov_b32_dpp v23, v22 row_ror:12 row_mask:0xf bank_mask:0x5
	v_readlane_b32 s20, v250, 57
	v_readlane_b32 s21, v250, 58
	v_readlane_b32 s24, v250, 61
	v_readlane_b32 s25, v250, 62
	s_waitcnt lgkmcnt(0)
	v_add_f32_e32 v22, v22, v23
	s_nop 1
	v_mov_b32_dpp v23, v22 quad_perm:[2,3,0,1] row_mask:0xf bank_mask:0xf
	v_readlane_b32 s26, v250, 63
	v_readlane_b32 s27, v249, 0
	v_readlane_b32 s28, v249, 1
	v_readlane_b32 s29, v249, 2
	s_waitcnt lgkmcnt(0)
	v_add_f32_e32 v30, v22, v23
	s_nop 1
	v_mov_b32_dpp v31, v30 quad_perm:[1,0,3,2] row_mask:0xf bank_mask:0xf
	v_cndmask_b32_e32 v22, v25, v64, vcc
	v_cndmask_b32_e32 v25, v26, v27, vcc
	v_cndmask_b32_e32 v23, 0, v24, vcc
	v_cndmask_b32_e32 v24, v28, v29, vcc
	s_waitcnt lgkmcnt(0)
	v_add_f32_e32 v26, v30, v31
	v_fmamk_f32 v26, v26, 0x3a800000, v198
	v_mul_f32_e32 v27, 0x4b800000, v26
	v_cmp_gt_f32_e32 vcc, s51, v26
	v_lshlrev_b64 v[22:23], 11, v[22:23]
	v_lshl_add_u64 v[22:23], v[24:25], 0, v[22:23]
	v_cndmask_b32_e32 v26, v26, v27, vcc
	v_rsq_f32_e32 v26, v26
	v_lshl_add_u64 v[22:23], v[22:23], 0, v[56:57]
	v_readlane_b32 s30, v249, 3
	v_readlane_b32 s31, v249, 4
	v_mul_f32_e32 v24, 0x45800000, v26
	v_cndmask_b32_e32 v24, v26, v24, vcc
	v_pk_mul_f32 v[12:13], v[12:13], v[24:25] op_sel_hi:[1,0]
	v_pk_mul_f32 v[14:15], v[14:15], v[24:25] op_sel_hi:[1,0]
	v_pk_mul_f32 v[8:9], v[8:9], v[24:25] op_sel_hi:[1,0]
	s_waitcnt vmcnt(0)
	v_pk_mul_f32 v[12:13], v[16:17], v[12:13]
	v_pk_mul_f32 v[14:15], v[18:19], v[14:15]
	v_cvt_pk_bf16_f32 v12, v12, v13
	v_cvt_pk_bf16_f32 v13, v14, v15
	global_store_dwordx2 v[22:23], v[12:13], off
	global_load_dwordx4 v[12:15], v[20:21], off offset:1024
	v_pk_mul_f32 v[10:11], v[10:11], v[24:25] op_sel_hi:[1,0]
	v_pk_mul_f32 v[4:5], v[4:5], v[24:25] op_sel_hi:[1,0]
	v_pk_mul_f32 v[6:7], v[6:7], v[24:25] op_sel_hi:[1,0]
	v_pk_mul_f32 v[0:1], v[0:1], v[24:25] op_sel_hi:[1,0]
	v_pk_mul_f32 v[2:3], v[2:3], v[24:25] op_sel_hi:[1,0]
	s_waitcnt vmcnt(0)
	v_pk_mul_f32 v[8:9], v[12:13], v[8:9]
	v_pk_mul_f32 v[10:11], v[14:15], v[10:11]
	v_cvt_pk_bf16_f32 v8, v8, v9
	v_cvt_pk_bf16_f32 v9, v10, v11
	global_store_dwordx2 v[22:23], v[8:9], off offset:512
	global_load_dwordx4 v[8:11], v[20:21], off offset:2048
	s_waitcnt vmcnt(0)
	v_pk_mul_f32 v[4:5], v[4:5], v[8:9]
	v_pk_mul_f32 v[6:7], v[6:7], v[10:11]
	v_cvt_pk_bf16_f32 v4, v4, v5
	v_cvt_pk_bf16_f32 v5, v6, v7
	global_store_dwordx2 v[22:23], v[4:5], off offset:1024
	global_load_dwordx4 v[4:7], v[20:21], off offset:3072
	s_waitcnt vmcnt(0)
	v_pk_mul_f32 v[0:1], v[0:1], v[4:5]
	v_pk_mul_f32 v[2:3], v[2:3], v[6:7]
	v_cvt_pk_bf16_f32 v0, v0, v1
	v_cvt_pk_bf16_f32 v1, v2, v3
	global_store_dwordx2 v[22:23], v[0:1], off offset:1536
	s_branch .LBB0_526
